# v27 + hand-written short-conv (CONVSC) row loop: scalar row bases, hoisted conv weights, all 28 loads per row in flight, boundary rows via masks and state-store variant
# speedup vs baseline: 1.0143x; 1.0143x over previous
; DI float bflo(unsigned u) { return __uint_as_float(u << 16); }
; DI float bfhi(unsigned u) { return __uint_as_float(u & 0xffff0000u); }
; DI void row_decode(int r, int& b, int& s) { if (r < RP) { b = r >> 11; s = r & 2047; } else { const int rr = r - RP; b = 16 + (rr >> 4); s = rr & 15; } }
; DI void phase_convsc(ArgsP AP) {
;     int tid = threadIdx.x; asm volatile("" : "+v"(tid)); const int lane = tid & 63, wave = tid >> 6;
;     const int gw = blockIdx.x * 8 + wave, NGW = gridDim.x * 8;
;     const bf16* BCX = (const bf16*)(AP->ws + WS_BIG); bf16* OA = (bf16*)(AP->ws + WS_BIG + 3 * U1);
;     const float* st = AP->in[4]; const float* cw = AP->in[24];
;     for (int r = gw; r < RT; r += NGW) {
;         int b, s; row_decode(r, b, s); const bool samp = r >= RP; const int slen = samp ? SSEQ : SEQ;
; #pragma unroll
;         for (int j = 0; j < 4; ++j) {
;             const int c = lane * 4 + 256 * j;
;             f32x4 cx[3];
; #pragma unroll
;             for (int d = 0; d < 3; ++d) {
;                 if (s - d >= 0) { const bf16* p = BCX + (size_t)(r - d) * 3072 + c; const u32x2 cc = *(const u32x2*)(p + 1024), xx = *(const u32x2*)(p + 2048);
;                     cx[d] = (f32x4){bflo(cc.x) * bflo(xx.x), bfhi(cc.x) * bfhi(xx.x), bflo(cc.y) * bflo(xx.y), bfhi(cc.y) * bfhi(xx.y)}; }
;                 else if (samp) cx[d] = *(const f32x4*)(st + ((size_t)(b - 16) * 2 + (2 + s - d)) * DM + c);
;                 else cx[d] = (f32x4){0.f, 0.f, 0.f, 0.f};
;             }
;             const f32x4 w0 = *(const f32x4*)(cw + c), w1 = *(const f32x4*)(cw + 1024 + c), w2 = *(const f32x4*)(cw + 2048 + c);
.LBB0_90:
	s_and_b64 vcc, exec, s[0:1]
	s_cbranch_vccz .LBB0_214
	s_cmp_gt_i32 s8, 5
	s_mov_b64 s[0:1], -1
	s_cbranch_scc0 .LBB0_154
	v_mov_b32_e32 v0, v164
	v_readlane_b32 s0, v253, 3
	v_ashrrev_i32_e32 v1, 6, v0
	s_nop 0
	v_add_u32_e32 v12, s0, v1
	s_mov_b32 s0, 0x8080
	v_cmp_gt_i32_e32 vcc, s0, v12
	s_and_saveexec_b64 s[0:1], vcc
	s_waitcnt lgkmcnt(0)
	s_load_dwordx2 s[24:25], s[86:87], 0x108
	v_readlane_b32 s6, v254, 43
	v_readlane_b32 s7, v254, 44
	v_readlane_b32 s22, v254, 49
	s_mov_b32 s7, 0x807f
	v_readlane_b32 s23, v254, 50
	s_cbranch_execz .LBB0_153
	s_load_dwordx2 s[2:3], s[86:87], 0x20
	s_load_dwordx2 s[8:9], s[86:87], 0xc0
	s_waitcnt lgkmcnt(0)
	s_add_u32 s14, s24, 0xaa00000
	s_addc_u32 s15, s25, 0
	v_lshlrev_b32_e32 v1, 2, v0
	v_and_b32_e32 v14, 0xfc, v1
	s_add_u32 s16, s8, 0x1000
	s_addc_u32 s17, s9, 0
	s_add_u32 s20, s8, 0x2000
	v_lshlrev_b32_e32 v2, 1, v14
	v_mov_b32_e32 v3, v97
	s_addc_u32 s21, s9, 0
	v_lshl_add_u64 v[16:17], s[14:15], 0, v[2:3]
	v_lshlrev_b32_e32 v2, 2, v14
	v_or_b32_e32 v1, 0x100, v14
	v_lshl_add_u64 v[18:19], s[8:9], 0, v[2:3]
	v_lshl_add_u64 v[20:21], s[16:17], 0, v[2:3]
	v_lshl_add_u64 v[22:23], s[20:21], 0, v[2:3]
	v_lshlrev_b32_e32 v4, 2, v1
	v_mov_b32_e32 v5, v97
	v_or_b32_e32 v6, 0x200, v14
	v_lshl_add_u64 v[36:37], s[2:3], 0, v[2:3]
	v_lshlrev_b32_e32 v2, 1, v1
	v_and_b32_e32 v0, 63, v0
	v_ashrrev_i32_e32 v13, 31, v12
	v_lshl_add_u64 v[24:25], s[16:17], 0, v[4:5]
	v_lshl_add_u64 v[26:27], s[20:21], 0, v[4:5]
	v_lshlrev_b32_e32 v4, 2, v6
	v_or_b32_e32 v7, 0x300, v14
	v_lshl_add_u64 v[38:39], s[14:15], 0, v[2:3]
	v_lshlrev_b32_e32 v2, 1, v6
	v_lshlrev_b32_e32 v44, 3, v0
	v_lshlrev_b64 v[0:1], 11, v[12:13]
	v_lshl_add_u64 v[28:29], s[16:17], 0, v[4:5]
	v_lshl_add_u64 v[30:31], s[20:21], 0, v[4:5]
	v_lshlrev_b32_e32 v4, 2, v7
	v_lshl_add_u64 v[40:41], s[14:15], 0, v[2:3]
	v_lshlrev_b32_e32 v2, 1, v7
	v_lshl_add_u64 v[46:47], s[24:25], 0, v[0:1]
	v_mov_b64_e32 v[0:1], s[24:25]
	v_lshl_add_u64 v[32:33], s[16:17], 0, v[4:5]
	v_lshl_add_u64 v[34:35], s[20:21], 0, v[4:5]
	v_lshl_add_u64 v[42:43], s[14:15], 0, v[2:3]
	v_mov_b32_e32 v45, v97
	v_mad_i64_i32 v[48:49], s[2:3], v12, s69, v[0:1]
	v_readfirstlane_b32 s36, v12
	v_readlane_b32 s40, v254, 43
	s_nop 0
	s_cmpk_lg_u32 s40, 0x800
	s_cbranch_scc1 .Lcsc_slow
	v_lshlrev_b32_e32 v99, 1, v44
	v_add_u32_e32 v98, 0x1000, v44
	global_load_dwordx4 v[100:103], v99, s[8:9]
	global_load_dwordx4 v[116:119], v99, s[16:17]
	global_load_dwordx4 v[132:135], v99, s[20:21]
	global_load_dwordx4 v[104:107], v99, s[8:9] offset:1024
	global_load_dwordx4 v[120:123], v99, s[16:17] offset:1024
	global_load_dwordx4 v[136:139], v99, s[20:21] offset:1024
	global_load_dwordx4 v[108:111], v99, s[8:9] offset:2048
	global_load_dwordx4 v[124:127], v99, s[16:17] offset:2048
	global_load_dwordx4 v[140:143], v99, s[20:21] offset:2048
	global_load_dwordx4 v[112:115], v99, s[8:9] offset:3072
	global_load_dwordx4 v[128:131], v99, s[16:17] offset:3072
	global_load_dwordx4 v[144:147], v99, s[20:21] offset:3072
	s_mul_i32 s37, s36, 0x1800
	s_add_u32 s26, s24, 0xaa00000
	s_addc_u32 s27, s25, 0
	s_add_u32 s26, s26, s37
	s_addc_u32 s27, s27, 0
	s_cmp_gt_u32 s36, 0
	s_cselect_b32 s40, 0x1800, 0
	s_cselect_b32 s44, 1.0, 0
	s_sub_u32 s28, s26, s40
	s_subb_u32 s29, s27, 0
	s_cmp_gt_u32 s36, 1
	s_cselect_b32 s40, 0x3000, 0
	s_cselect_b32 s45, 1.0, 0
	s_sub_u32 s30, s26, s40
	s_subb_u32 s31, s27, 0
	v_mov_b32_e32 v94, s44
	v_mov_b32_e32 v95, s45
	s_lshl_b32 s37, s36, 11
	s_add_u32 s34, s24, 0x16b80000
	s_addc_u32 s35, s25, 0
	s_add_u32 s34, s34, s37
	s_addc_u32 s35, s35, 0
	s_mov_b32 s37, 0
	s_cmpk_gt_u32 s36, 0x7fd
	s_cbranch_scc1 .Lcsc_state
	global_load_dwordx2 v[148:149], v44, s[26:27]
	global_load_dwordx2 v[150:151], v44, s[26:27] offset:2048
	global_load_dwordx2 v[152:153], v98, s[26:27]
	global_load_dwordx2 v[154:155], v44, s[28:29] offset:2048
	global_load_dwordx2 v[156:157], v98, s[28:29]
	global_load_dwordx2 v[158:159], v44, s[30:31] offset:2048
	global_load_dwordx2 v[160:161], v98, s[30:31]
	global_load_dwordx2 v[228:229], v44, s[26:27]
	global_load_dwordx2 v[168:169], v44, s[26:27] offset:512
	global_load_dwordx2 v[170:171], v44, s[26:27] offset:2560
	global_load_dwordx2 v[172:173], v98, s[26:27] offset:512
	global_load_dwordx2 v[174:175], v44, s[28:29] offset:2560
	global_load_dwordx2 v[176:177], v98, s[28:29] offset:512
	global_load_dwordx2 v[178:179], v44, s[30:31] offset:2560
	global_load_dwordx2 v[180:181], v98, s[30:31] offset:512
	global_load_dwordx2 v[228:229], v44, s[26:27]
	global_load_dwordx2 v[182:183], v44, s[26:27] offset:1024
	global_load_dwordx2 v[184:185], v44, s[26:27] offset:3072
	global_load_dwordx2 v[186:187], v98, s[26:27] offset:1024
	global_load_dwordx2 v[188:189], v44, s[28:29] offset:3072
	global_load_dwordx2 v[190:191], v98, s[28:29] offset:1024
	global_load_dwordx2 v[192:193], v44, s[30:31] offset:3072
	global_load_dwordx2 v[194:195], v98, s[30:31] offset:1024
	global_load_dwordx2 v[228:229], v44, s[26:27]
	global_load_dwordx2 v[196:197], v44, s[26:27] offset:1536
	global_load_dwordx2 v[198:199], v44, s[26:27] offset:3584
	global_load_dwordx2 v[200:201], v98, s[26:27] offset:1536
	global_load_dwordx2 v[202:203], v44, s[28:29] offset:3584
	global_load_dwordx2 v[204:205], v98, s[28:29] offset:1536
	global_load_dwordx2 v[206:207], v44, s[30:31] offset:3584
	global_load_dwordx2 v[208:209], v98, s[30:31] offset:1536
; DI unsigned pk2(float lo, float hi) { f32x2 v = {lo, hi}; bf16x2_t b = __builtin_convertvector(v, bf16x2_t); return __builtin_bit_cast(unsigned, b); }
; DI float bflo(unsigned u) { return __uint_as_float(u << 16); }
; DI float bfhi(unsigned u) { return __uint_as_float(u & 0xffff0000u); }
; DI void row_decode(int r, int& b, int& s) { if (r < RP) { b = r >> 11; s = r & 2047; } else { const int rr = r - RP; b = 16 + (rr >> 4); s = rr & 15; } }
; DI void phase_convsc(ArgsP AP) {
;     ...
;         int b, s; row_decode(r, b, s); const bool samp = r >= RP; const int slen = samp ? SSEQ : SEQ;
; #pragma unroll
;         for (int j = 0; j < 4; ++j) {
;             const int c = lane * 4 + 256 * j;
;             f32x4 cx[3];
; #pragma unroll
;             for (int d = 0; d < 3; ++d) {
;                 if (s - d >= 0) { const bf16* p = BCX + (size_t)(r - d) * 3072 + c; const u32x2 cc = *(const u32x2*)(p + 1024), xx = *(const u32x2*)(p + 2048);
;                     cx[d] = (f32x4){bflo(cc.x) * bflo(xx.x), bfhi(cc.x) * bfhi(xx.x), bflo(cc.y) * bflo(xx.y), bfhi(cc.y) * bfhi(xx.y)}; }
;                 else if (samp) cx[d] = *(const f32x4*)(st + ((size_t)(b - 16) * 2 + (2 + s - d)) * DM + c);
;                 else cx[d] = (f32x4){0.f, 0.f, 0.f, 0.f};
;             }
;             const f32x4 w0 = *(const f32x4*)(cw + c), w1 = *(const f32x4*)(cw + 1024 + c), w2 = *(const f32x4*)(cw + 2048 + c);
;             const f32x4 y = w2 * cx[0] + w1 * cx[1] + w0 * cx[2];
;             const u32x2 bg = *(const u32x2*)(BCX + (size_t)r * 3072 + c);
;             u32x2 w; w.x = pk2(bflo(bg.x) * y[0], bfhi(bg.x) * y[1]); w.y = pk2(bflo(bg.y) * y[2], bfhi(bg.y) * y[3]);
;             *(u32x2*)(OA + (size_t)r * DM + c) = w;
.Lcsc_row_n:
	s_cmp_lt_u32 s37, 15
	s_cselect_b32 s40, 0xc00000, 0
	s_add_u32 s26, s26, s40
	s_addc_u32 s27, s27, 0
	s_add_u32 s28, s28, s40
	s_addc_u32 s29, s29, 0
	s_add_u32 s30, s30, s40
	s_addc_u32 s31, s31, 0
	s_waitcnt vmcnt(24)
	v_lshlrev_b32_e32 v78, 16, v150
	v_and_b32_e32 v79, 0xffff0000, v150
	v_lshlrev_b32_e32 v80, 16, v151
	v_and_b32_e32 v81, 0xffff0000, v151
	v_lshlrev_b32_e32 v82, 16, v152
	v_and_b32_e32 v83, 0xffff0000, v152
	v_lshlrev_b32_e32 v84, 16, v153
	v_and_b32_e32 v85, 0xffff0000, v153
	v_pk_mul_f32 v[86:87], v[78:79], v[82:83]
	v_pk_mul_f32 v[88:89], v[80:81], v[84:85]
	v_lshlrev_b32_e32 v78, 16, v154
	v_and_b32_e32 v79, 0xffff0000, v154
	v_lshlrev_b32_e32 v80, 16, v155
	v_and_b32_e32 v81, 0xffff0000, v155
	v_lshlrev_b32_e32 v82, 16, v156
	v_and_b32_e32 v83, 0xffff0000, v156
	v_lshlrev_b32_e32 v84, 16, v157
	v_and_b32_e32 v85, 0xffff0000, v157
	v_pk_mul_f32 v[90:91], v[78:79], v[82:83]
	v_pk_mul_f32 v[92:93], v[80:81], v[84:85]
	v_lshlrev_b32_e32 v78, 16, v158
	v_and_b32_e32 v79, 0xffff0000, v158
	v_lshlrev_b32_e32 v80, 16, v159
	v_and_b32_e32 v81, 0xffff0000, v159
	v_lshlrev_b32_e32 v82, 16, v160
	v_and_b32_e32 v83, 0xffff0000, v160
	v_lshlrev_b32_e32 v84, 16, v161
	v_and_b32_e32 v85, 0xffff0000, v161
	v_pk_mul_f32 v[210:211], v[78:79], v[82:83]
	v_pk_mul_f32 v[212:213], v[80:81], v[84:85]
	v_pk_mul_f32 v[90:91], v[90:91], v[94:95] op_sel_hi:[1,0]
	v_pk_mul_f32 v[92:93], v[92:93], v[94:95] op_sel_hi:[1,0]
	v_pk_mul_f32 v[210:211], v[210:211], v[94:95] op_sel:[0,1]
	v_pk_mul_f32 v[212:213], v[212:213], v[94:95] op_sel:[0,1]
	v_lshlrev_b32_e32 v78, 16, v148
	v_and_b32_e32 v79, 0xffff0000, v148
	v_lshlrev_b32_e32 v80, 16, v149
	v_and_b32_e32 v81, 0xffff0000, v149
	v_pk_mul_f32 v[214:215], v[86:87], v[132:133]
	v_pk_mul_f32 v[216:217], v[88:89], v[134:135]
	s_nop 0
	v_pk_fma_f32 v[214:215], v[90:91], v[116:117], v[214:215]
	v_pk_fma_f32 v[216:217], v[92:93], v[118:119], v[216:217]
	s_nop 0
	v_pk_fma_f32 v[214:215], v[210:211], v[100:101], v[214:215]
	v_pk_fma_f32 v[216:217], v[212:213], v[102:103], v[216:217]
	s_nop 0
	v_pk_mul_f32 v[214:215], v[214:215], v[78:79]
	v_pk_mul_f32 v[216:217], v[216:217], v[80:81]
	s_nop 0
	v_cvt_pk_bf16_f32 v218, v214, v215
	v_cvt_pk_bf16_f32 v219, v216, v217
	global_store_dwordx2 v44, v[218:219], s[34:35]
	global_load_dwordx2 v[148:149], v44, s[26:27]
	global_load_dwordx2 v[150:151], v44, s[26:27] offset:2048
	global_load_dwordx2 v[152:153], v98, s[26:27]
	global_load_dwordx2 v[154:155], v44, s[28:29] offset:2048
	global_load_dwordx2 v[156:157], v98, s[28:29]
	global_load_dwordx2 v[158:159], v44, s[30:31] offset:2048
	global_load_dwordx2 v[160:161], v98, s[30:31]
	s_waitcnt vmcnt(24)
	v_lshlrev_b32_e32 v78, 16, v170
	v_and_b32_e32 v79, 0xffff0000, v170
	v_lshlrev_b32_e32 v80, 16, v171
	v_and_b32_e32 v81, 0xffff0000, v171
	v_lshlrev_b32_e32 v82, 16, v172
	v_and_b32_e32 v83, 0xffff0000, v172
	v_lshlrev_b32_e32 v84, 16, v173
	v_and_b32_e32 v85, 0xffff0000, v173
	v_pk_mul_f32 v[86:87], v[78:79], v[82:83]
	v_pk_mul_f32 v[88:89], v[80:81], v[84:85]
	v_lshlrev_b32_e32 v78, 16, v174
	v_and_b32_e32 v79, 0xffff0000, v174
	v_lshlrev_b32_e32 v80, 16, v175
	v_and_b32_e32 v81, 0xffff0000, v175
	v_lshlrev_b32_e32 v82, 16, v176
	v_and_b32_e32 v83, 0xffff0000, v176
	v_lshlrev_b32_e32 v84, 16, v177
	v_and_b32_e32 v85, 0xffff0000, v177
	v_pk_mul_f32 v[90:91], v[78:79], v[82:83]
	v_pk_mul_f32 v[92:93], v[80:81], v[84:85]
	v_lshlrev_b32_e32 v78, 16, v178
	v_and_b32_e32 v79, 0xffff0000, v178
	v_lshlrev_b32_e32 v80, 16, v179
	v_and_b32_e32 v81, 0xffff0000, v179
	v_lshlrev_b32_e32 v82, 16, v180
	v_and_b32_e32 v83, 0xffff0000, v180
	v_lshlrev_b32_e32 v84, 16, v181
	v_and_b32_e32 v85, 0xffff0000, v181
	v_pk_mul_f32 v[210:211], v[78:79], v[82:83]
	v_pk_mul_f32 v[212:213], v[80:81], v[84:85]
	v_pk_mul_f32 v[90:91], v[90:91], v[94:95] op_sel_hi:[1,0]
	v_pk_mul_f32 v[92:93], v[92:93], v[94:95] op_sel_hi:[1,0]
	v_pk_mul_f32 v[210:211], v[210:211], v[94:95] op_sel:[0,1]
	v_pk_mul_f32 v[212:213], v[212:213], v[94:95] op_sel:[0,1]
	v_lshlrev_b32_e32 v78, 16, v168
	v_and_b32_e32 v79, 0xffff0000, v168
	v_lshlrev_b32_e32 v80, 16, v169
	v_and_b32_e32 v81, 0xffff0000, v169
	v_pk_mul_f32 v[214:215], v[86:87], v[136:137]
	v_pk_mul_f32 v[216:217], v[88:89], v[138:139]
	s_nop 0
	v_pk_fma_f32 v[214:215], v[90:91], v[120:121], v[214:215]
	v_pk_fma_f32 v[216:217], v[92:93], v[122:123], v[216:217]
	s_nop 0
	v_pk_fma_f32 v[214:215], v[210:211], v[104:105], v[214:215]
	v_pk_fma_f32 v[216:217], v[212:213], v[106:107], v[216:217]
	s_nop 0
	v_pk_mul_f32 v[214:215], v[214:215], v[78:79]
	v_pk_mul_f32 v[216:217], v[216:217], v[80:81]
	s_nop 0
	v_cvt_pk_bf16_f32 v218, v214, v215
	v_cvt_pk_bf16_f32 v219, v216, v217
	global_store_dwordx2 v44, v[218:219], s[34:35] offset:512
	global_load_dwordx2 v[168:169], v44, s[26:27] offset:512
	global_load_dwordx2 v[170:171], v44, s[26:27] offset:2560
	global_load_dwordx2 v[172:173], v98, s[26:27] offset:512
	global_load_dwordx2 v[174:175], v44, s[28:29] offset:2560
	global_load_dwordx2 v[176:177], v98, s[28:29] offset:512
	global_load_dwordx2 v[178:179], v44, s[30:31] offset:2560
	global_load_dwordx2 v[180:181], v98, s[30:31] offset:512
	s_waitcnt vmcnt(24)
; DI unsigned pk2(float lo, float hi) { f32x2 v = {lo, hi}; bf16x2_t b = __builtin_convertvector(v, bf16x2_t); return __builtin_bit_cast(unsigned, b); }
; DI float bflo(unsigned u) { return __uint_as_float(u << 16); }
; DI float bfhi(unsigned u) { return __uint_as_float(u & 0xffff0000u); }
; DI void phase_convsc(ArgsP AP) {
;     ...
;         for (int j = 0; j < 4; ++j) {
;             const int c = lane * 4 + 256 * j;
;             f32x4 cx[3];
; #pragma unroll
;             for (int d = 0; d < 3; ++d) {
;                 if (s - d >= 0) { const bf16* p = BCX + (size_t)(r - d) * 3072 + c; const u32x2 cc = *(const u32x2*)(p + 1024), xx = *(const u32x2*)(p + 2048);
;                     cx[d] = (f32x4){bflo(cc.x) * bflo(xx.x), bfhi(cc.x) * bfhi(xx.x), bflo(cc.y) * bflo(xx.y), bfhi(cc.y) * bfhi(xx.y)}; }
;                 else if (samp) cx[d] = *(const f32x4*)(st + ((size_t)(b - 16) * 2 + (2 + s - d)) * DM + c);
;                 else cx[d] = (f32x4){0.f, 0.f, 0.f, 0.f};
;             }
;             const f32x4 w0 = *(const f32x4*)(cw + c), w1 = *(const f32x4*)(cw + 1024 + c), w2 = *(const f32x4*)(cw + 2048 + c);
;             const f32x4 y = w2 * cx[0] + w1 * cx[1] + w0 * cx[2];
;             const u32x2 bg = *(const u32x2*)(BCX + (size_t)r * 3072 + c);
;             u32x2 w; w.x = pk2(bflo(bg.x) * y[0], bfhi(bg.x) * y[1]); w.y = pk2(bflo(bg.y) * y[2], bfhi(bg.y) * y[3]);
;             *(u32x2*)(OA + (size_t)r * DM + c) = w;
	v_lshlrev_b32_e32 v78, 16, v184
	v_and_b32_e32 v79, 0xffff0000, v184
	v_lshlrev_b32_e32 v80, 16, v185
	v_and_b32_e32 v81, 0xffff0000, v185
	v_lshlrev_b32_e32 v82, 16, v186
	v_and_b32_e32 v83, 0xffff0000, v186
	v_lshlrev_b32_e32 v84, 16, v187
	v_and_b32_e32 v85, 0xffff0000, v187
	v_pk_mul_f32 v[86:87], v[78:79], v[82:83]
	v_pk_mul_f32 v[88:89], v[80:81], v[84:85]
	v_lshlrev_b32_e32 v78, 16, v188
	v_and_b32_e32 v79, 0xffff0000, v188
	v_lshlrev_b32_e32 v80, 16, v189
	v_and_b32_e32 v81, 0xffff0000, v189
	v_lshlrev_b32_e32 v82, 16, v190
	v_and_b32_e32 v83, 0xffff0000, v190
	v_lshlrev_b32_e32 v84, 16, v191
	v_and_b32_e32 v85, 0xffff0000, v191
	v_pk_mul_f32 v[90:91], v[78:79], v[82:83]
	v_pk_mul_f32 v[92:93], v[80:81], v[84:85]
	v_lshlrev_b32_e32 v78, 16, v192
	v_and_b32_e32 v79, 0xffff0000, v192
	v_lshlrev_b32_e32 v80, 16, v193
	v_and_b32_e32 v81, 0xffff0000, v193
	v_lshlrev_b32_e32 v82, 16, v194
	v_and_b32_e32 v83, 0xffff0000, v194
	v_lshlrev_b32_e32 v84, 16, v195
	v_and_b32_e32 v85, 0xffff0000, v195
	v_pk_mul_f32 v[210:211], v[78:79], v[82:83]
	v_pk_mul_f32 v[212:213], v[80:81], v[84:85]
	v_pk_mul_f32 v[90:91], v[90:91], v[94:95] op_sel_hi:[1,0]
	v_pk_mul_f32 v[92:93], v[92:93], v[94:95] op_sel_hi:[1,0]
	v_pk_mul_f32 v[210:211], v[210:211], v[94:95] op_sel:[0,1]
	v_pk_mul_f32 v[212:213], v[212:213], v[94:95] op_sel:[0,1]
	v_lshlrev_b32_e32 v78, 16, v182
	v_and_b32_e32 v79, 0xffff0000, v182
	v_lshlrev_b32_e32 v80, 16, v183
	v_and_b32_e32 v81, 0xffff0000, v183
	v_pk_mul_f32 v[214:215], v[86:87], v[140:141]
	v_pk_mul_f32 v[216:217], v[88:89], v[142:143]
	s_nop 0
	v_pk_fma_f32 v[214:215], v[90:91], v[124:125], v[214:215]
	v_pk_fma_f32 v[216:217], v[92:93], v[126:127], v[216:217]
	s_nop 0
	v_pk_fma_f32 v[214:215], v[210:211], v[108:109], v[214:215]
	v_pk_fma_f32 v[216:217], v[212:213], v[110:111], v[216:217]
	s_nop 0
	v_pk_mul_f32 v[214:215], v[214:215], v[78:79]
	v_pk_mul_f32 v[216:217], v[216:217], v[80:81]
	s_nop 0
	v_cvt_pk_bf16_f32 v218, v214, v215
	v_cvt_pk_bf16_f32 v219, v216, v217
	global_store_dwordx2 v44, v[218:219], s[34:35] offset:1024
	global_load_dwordx2 v[182:183], v44, s[26:27] offset:1024
	global_load_dwordx2 v[184:185], v44, s[26:27] offset:3072
	global_load_dwordx2 v[186:187], v98, s[26:27] offset:1024
	global_load_dwordx2 v[188:189], v44, s[28:29] offset:3072
	global_load_dwordx2 v[190:191], v98, s[28:29] offset:1024
	global_load_dwordx2 v[192:193], v44, s[30:31] offset:3072
	global_load_dwordx2 v[194:195], v98, s[30:31] offset:1024
	s_waitcnt vmcnt(24)
	v_lshlrev_b32_e32 v78, 16, v198
	v_and_b32_e32 v79, 0xffff0000, v198
	v_lshlrev_b32_e32 v80, 16, v199
	v_and_b32_e32 v81, 0xffff0000, v199
	v_lshlrev_b32_e32 v82, 16, v200
	v_and_b32_e32 v83, 0xffff0000, v200
	v_lshlrev_b32_e32 v84, 16, v201
	v_and_b32_e32 v85, 0xffff0000, v201
	v_pk_mul_f32 v[86:87], v[78:79], v[82:83]
	v_pk_mul_f32 v[88:89], v[80:81], v[84:85]
	v_lshlrev_b32_e32 v78, 16, v202
	v_and_b32_e32 v79, 0xffff0000, v202
	v_lshlrev_b32_e32 v80, 16, v203
	v_and_b32_e32 v81, 0xffff0000, v203
	v_lshlrev_b32_e32 v82, 16, v204
	v_and_b32_e32 v83, 0xffff0000, v204
	v_lshlrev_b32_e32 v84, 16, v205
	v_and_b32_e32 v85, 0xffff0000, v205
	v_pk_mul_f32 v[90:91], v[78:79], v[82:83]
	v_pk_mul_f32 v[92:93], v[80:81], v[84:85]
	v_lshlrev_b32_e32 v78, 16, v206
	v_and_b32_e32 v79, 0xffff0000, v206
	v_lshlrev_b32_e32 v80, 16, v207
	v_and_b32_e32 v81, 0xffff0000, v207
	v_lshlrev_b32_e32 v82, 16, v208
	v_and_b32_e32 v83, 0xffff0000, v208
	v_lshlrev_b32_e32 v84, 16, v209
	v_and_b32_e32 v85, 0xffff0000, v209
	v_pk_mul_f32 v[210:211], v[78:79], v[82:83]
	v_pk_mul_f32 v[212:213], v[80:81], v[84:85]
	v_pk_mul_f32 v[90:91], v[90:91], v[94:95] op_sel_hi:[1,0]
	v_pk_mul_f32 v[92:93], v[92:93], v[94:95] op_sel_hi:[1,0]
	v_pk_mul_f32 v[210:211], v[210:211], v[94:95] op_sel:[0,1]
	v_pk_mul_f32 v[212:213], v[212:213], v[94:95] op_sel:[0,1]
	v_lshlrev_b32_e32 v78, 16, v196
	v_and_b32_e32 v79, 0xffff0000, v196
	v_lshlrev_b32_e32 v80, 16, v197
	v_and_b32_e32 v81, 0xffff0000, v197
	v_pk_mul_f32 v[214:215], v[86:87], v[144:145]
	v_pk_mul_f32 v[216:217], v[88:89], v[146:147]
	s_nop 0
	v_pk_fma_f32 v[214:215], v[90:91], v[128:129], v[214:215]
	v_pk_fma_f32 v[216:217], v[92:93], v[130:131], v[216:217]
	s_nop 0
	v_pk_fma_f32 v[214:215], v[210:211], v[112:113], v[214:215]
	v_pk_fma_f32 v[216:217], v[212:213], v[114:115], v[216:217]
	s_nop 0
	v_pk_mul_f32 v[214:215], v[214:215], v[78:79]
	v_pk_mul_f32 v[216:217], v[216:217], v[80:81]
	s_nop 0
	v_cvt_pk_bf16_f32 v218, v214, v215
	v_cvt_pk_bf16_f32 v219, v216, v217
	global_store_dwordx2 v44, v[218:219], s[34:35] offset:1536
	global_load_dwordx2 v[196:197], v44, s[26:27] offset:1536
	global_load_dwordx2 v[198:199], v44, s[26:27] offset:3584
	global_load_dwordx2 v[200:201], v98, s[26:27] offset:1536
	global_load_dwordx2 v[202:203], v44, s[28:29] offset:3584
	global_load_dwordx2 v[204:205], v98, s[28:29] offset:1536
	global_load_dwordx2 v[206:207], v44, s[30:31] offset:3584
	global_load_dwordx2 v[208:209], v98, s[30:31] offset:1536
	s_add_u32 s34, s34, 0x400000
	s_addc_u32 s35, s35, 0
	s_add_i32 s37, s37, 1
	s_cmp_lt_u32 s37, 16
	s_cbranch_scc1 .Lcsc_row_n
	s_branch .Lcsc_tail
; DI unsigned pk2(float lo, float hi) { f32x2 v = {lo, hi}; bf16x2_t b = __builtin_convertvector(v, bf16x2_t); return __builtin_bit_cast(unsigned, b); }
; DI float bflo(unsigned u) { return __uint_as_float(u << 16); }
; DI float bfhi(unsigned u) { return __uint_as_float(u & 0xffff0000u); }
; DI void phase_convsc(ArgsP AP) {
;     ...
;                 if (s - d >= 0) { const bf16* p = BCX + (size_t)(r - d) * 3072 + c; const u32x2 cc = *(const u32x2*)(p + 1024), xx = *(const u32x2*)(p + 2048);
;                     cx[d] = (f32x4){bflo(cc.x) * bflo(xx.x), bfhi(cc.x) * bfhi(xx.x), bflo(cc.y) * bflo(xx.y), bfhi(cc.y) * bfhi(xx.y)}; }
;                 else if (samp) cx[d] = *(const f32x4*)(st + ((size_t)(b - 16) * 2 + (2 + s - d)) * DM + c);
;                 else cx[d] = (f32x4){0.f, 0.f, 0.f, 0.f};
;             }
;             const f32x4 w0 = *(const f32x4*)(cw + c), w1 = *(const f32x4*)(cw + 1024 + c), w2 = *(const f32x4*)(cw + 2048 + c);
;             const f32x4 y = w2 * cx[0] + w1 * cx[1] + w0 * cx[2];
;             const u32x2 bg = *(const u32x2*)(BCX + (size_t)r * 3072 + c);
;             u32x2 w; w.x = pk2(bflo(bg.x) * y[0], bfhi(bg.x) * y[1]); w.y = pk2(bflo(bg.y) * y[2], bfhi(bg.y) * y[3]);
;             *(u32x2*)(OA + (size_t)r * DM + c) = w;
;             if (s >= slen - 2) { float* o = samp ? AP->out + O_SCS + ((size_t)(b - 16) * 2 + (s - (slen - 2))) * DM + c : AP->out + O_SCP + ((size_t)b * 2 + (s - (slen - 2))) * DM + c; *(f32x4*)o = cx[0]; }
.Lcsc_state:
	s_load_dwordx2 s[42:43], s[86:87], 0x100
	s_sub_u32 s40, s36, 0x7fe
	s_lshl_b32 s40, s40, 12
	s_waitcnt lgkmcnt(0)
	s_add_u32 s42, s42, 0x18200000
	s_addc_u32 s43, s43, 0
	s_add_u32 s42, s42, s40
	s_addc_u32 s43, s43, 0
	global_load_dwordx2 v[148:149], v44, s[26:27]
	global_load_dwordx2 v[150:151], v44, s[26:27] offset:2048
	global_load_dwordx2 v[152:153], v98, s[26:27]
	global_load_dwordx2 v[154:155], v44, s[28:29] offset:2048
	global_load_dwordx2 v[156:157], v98, s[28:29]
	global_load_dwordx2 v[158:159], v44, s[30:31] offset:2048
	global_load_dwordx2 v[160:161], v98, s[30:31]
	global_load_dwordx2 v[228:229], v44, s[26:27]
	global_load_dwordx2 v[228:229], v44, s[26:27]
	global_load_dwordx2 v[168:169], v44, s[26:27] offset:512
	global_load_dwordx2 v[170:171], v44, s[26:27] offset:2560
	global_load_dwordx2 v[172:173], v98, s[26:27] offset:512
	global_load_dwordx2 v[174:175], v44, s[28:29] offset:2560
	global_load_dwordx2 v[176:177], v98, s[28:29] offset:512
	global_load_dwordx2 v[178:179], v44, s[30:31] offset:2560
	global_load_dwordx2 v[180:181], v98, s[30:31] offset:512
	global_load_dwordx2 v[228:229], v44, s[26:27]
	global_load_dwordx2 v[228:229], v44, s[26:27]
	global_load_dwordx2 v[182:183], v44, s[26:27] offset:1024
	global_load_dwordx2 v[184:185], v44, s[26:27] offset:3072
	global_load_dwordx2 v[186:187], v98, s[26:27] offset:1024
	global_load_dwordx2 v[188:189], v44, s[28:29] offset:3072
	global_load_dwordx2 v[190:191], v98, s[28:29] offset:1024
	global_load_dwordx2 v[192:193], v44, s[30:31] offset:3072
	global_load_dwordx2 v[194:195], v98, s[30:31] offset:1024
	global_load_dwordx2 v[228:229], v44, s[26:27]
	global_load_dwordx2 v[228:229], v44, s[26:27]
	global_load_dwordx2 v[196:197], v44, s[26:27] offset:1536
	global_load_dwordx2 v[198:199], v44, s[26:27] offset:3584
	global_load_dwordx2 v[200:201], v98, s[26:27] offset:1536
	global_load_dwordx2 v[202:203], v44, s[28:29] offset:3584
	global_load_dwordx2 v[204:205], v98, s[28:29] offset:1536
	global_load_dwordx2 v[206:207], v44, s[30:31] offset:3584
	global_load_dwordx2 v[208:209], v98, s[30:31] offset:1536
.Lcsc_row_s:
	s_cmp_lt_u32 s37, 15
	s_cselect_b32 s40, 0xc00000, 0
	s_add_u32 s26, s26, s40
	s_addc_u32 s27, s27, 0
	s_add_u32 s28, s28, s40
	s_addc_u32 s29, s29, 0
	s_add_u32 s30, s30, s40
	s_addc_u32 s31, s31, 0
	s_waitcnt vmcnt(27)
	v_lshlrev_b32_e32 v78, 16, v150
	v_and_b32_e32 v79, 0xffff0000, v150
	v_lshlrev_b32_e32 v80, 16, v151
	v_and_b32_e32 v81, 0xffff0000, v151
	v_lshlrev_b32_e32 v82, 16, v152
	v_and_b32_e32 v83, 0xffff0000, v152
	v_lshlrev_b32_e32 v84, 16, v153
	v_and_b32_e32 v85, 0xffff0000, v153
	v_pk_mul_f32 v[86:87], v[78:79], v[82:83]
	v_pk_mul_f32 v[88:89], v[80:81], v[84:85]
	v_lshlrev_b32_e32 v78, 16, v154
	v_and_b32_e32 v79, 0xffff0000, v154
	v_lshlrev_b32_e32 v80, 16, v155
	v_and_b32_e32 v81, 0xffff0000, v155
	v_lshlrev_b32_e32 v82, 16, v156
	v_and_b32_e32 v83, 0xffff0000, v156
	v_lshlrev_b32_e32 v84, 16, v157
	v_and_b32_e32 v85, 0xffff0000, v157
	v_pk_mul_f32 v[90:91], v[78:79], v[82:83]
	v_pk_mul_f32 v[92:93], v[80:81], v[84:85]
	v_lshlrev_b32_e32 v78, 16, v158
	v_and_b32_e32 v79, 0xffff0000, v158
	v_lshlrev_b32_e32 v80, 16, v159
	v_and_b32_e32 v81, 0xffff0000, v159
	v_lshlrev_b32_e32 v82, 16, v160
	v_and_b32_e32 v83, 0xffff0000, v160
	v_lshlrev_b32_e32 v84, 16, v161
	v_and_b32_e32 v85, 0xffff0000, v161
	v_pk_mul_f32 v[210:211], v[78:79], v[82:83]
	v_pk_mul_f32 v[212:213], v[80:81], v[84:85]
	global_store_dwordx4 v99, v[86:89], s[42:43]
	v_pk_mul_f32 v[90:91], v[90:91], v[94:95] op_sel_hi:[1,0]
	v_pk_mul_f32 v[92:93], v[92:93], v[94:95] op_sel_hi:[1,0]
	v_pk_mul_f32 v[210:211], v[210:211], v[94:95] op_sel:[0,1]
	v_pk_mul_f32 v[212:213], v[212:213], v[94:95] op_sel:[0,1]
	v_lshlrev_b32_e32 v78, 16, v148
	v_and_b32_e32 v79, 0xffff0000, v148
	v_lshlrev_b32_e32 v80, 16, v149
	v_and_b32_e32 v81, 0xffff0000, v149
	v_pk_mul_f32 v[214:215], v[86:87], v[132:133]
	v_pk_mul_f32 v[216:217], v[88:89], v[134:135]
	s_nop 0
	v_pk_fma_f32 v[214:215], v[90:91], v[116:117], v[214:215]
	v_pk_fma_f32 v[216:217], v[92:93], v[118:119], v[216:217]
	s_nop 0
	v_pk_fma_f32 v[214:215], v[210:211], v[100:101], v[214:215]
	v_pk_fma_f32 v[216:217], v[212:213], v[102:103], v[216:217]
	s_nop 0
	v_pk_mul_f32 v[214:215], v[214:215], v[78:79]
	v_pk_mul_f32 v[216:217], v[216:217], v[80:81]
	s_nop 0
	v_cvt_pk_bf16_f32 v218, v214, v215
	v_cvt_pk_bf16_f32 v219, v216, v217
	global_store_dwordx2 v44, v[218:219], s[34:35]
	global_load_dwordx2 v[148:149], v44, s[26:27]
	global_load_dwordx2 v[150:151], v44, s[26:27] offset:2048
	global_load_dwordx2 v[152:153], v98, s[26:27]
	global_load_dwordx2 v[154:155], v44, s[28:29] offset:2048
	global_load_dwordx2 v[156:157], v98, s[28:29]
	global_load_dwordx2 v[158:159], v44, s[30:31] offset:2048
	global_load_dwordx2 v[160:161], v98, s[30:31]
	s_waitcnt vmcnt(27)
; DI unsigned pk2(float lo, float hi) { f32x2 v = {lo, hi}; bf16x2_t b = __builtin_convertvector(v, bf16x2_t); return __builtin_bit_cast(unsigned, b); }
; DI float bflo(unsigned u) { return __uint_as_float(u << 16); }
; DI float bfhi(unsigned u) { return __uint_as_float(u & 0xffff0000u); }
; DI void phase_convsc(ArgsP AP) {
;     ...
;                 if (s - d >= 0) { const bf16* p = BCX + (size_t)(r - d) * 3072 + c; const u32x2 cc = *(const u32x2*)(p + 1024), xx = *(const u32x2*)(p + 2048);
;                     cx[d] = (f32x4){bflo(cc.x) * bflo(xx.x), bfhi(cc.x) * bfhi(xx.x), bflo(cc.y) * bflo(xx.y), bfhi(cc.y) * bfhi(xx.y)}; }
;                 else if (samp) cx[d] = *(const f32x4*)(st + ((size_t)(b - 16) * 2 + (2 + s - d)) * DM + c);
;                 else cx[d] = (f32x4){0.f, 0.f, 0.f, 0.f};
;             }
;             const f32x4 w0 = *(const f32x4*)(cw + c), w1 = *(const f32x4*)(cw + 1024 + c), w2 = *(const f32x4*)(cw + 2048 + c);
;             const f32x4 y = w2 * cx[0] + w1 * cx[1] + w0 * cx[2];
;             const u32x2 bg = *(const u32x2*)(BCX + (size_t)r * 3072 + c);
;             u32x2 w; w.x = pk2(bflo(bg.x) * y[0], bfhi(bg.x) * y[1]); w.y = pk2(bflo(bg.y) * y[2], bfhi(bg.y) * y[3]);
;             *(u32x2*)(OA + (size_t)r * DM + c) = w;
;             if (s >= slen - 2) { float* o = samp ? AP->out + O_SCS + ((size_t)(b - 16) * 2 + (s - (slen - 2))) * DM + c : AP->out + O_SCP + ((size_t)b * 2 + (s - (slen - 2))) * DM + c; *(f32x4*)o = cx[0]; }
	v_lshlrev_b32_e32 v78, 16, v170
	v_and_b32_e32 v79, 0xffff0000, v170
	v_lshlrev_b32_e32 v80, 16, v171
	v_and_b32_e32 v81, 0xffff0000, v171
	v_lshlrev_b32_e32 v82, 16, v172
	v_and_b32_e32 v83, 0xffff0000, v172
	v_lshlrev_b32_e32 v84, 16, v173
	v_and_b32_e32 v85, 0xffff0000, v173
	v_pk_mul_f32 v[86:87], v[78:79], v[82:83]
	v_pk_mul_f32 v[88:89], v[80:81], v[84:85]
	v_lshlrev_b32_e32 v78, 16, v174
	v_and_b32_e32 v79, 0xffff0000, v174
	v_lshlrev_b32_e32 v80, 16, v175
	v_and_b32_e32 v81, 0xffff0000, v175
	v_lshlrev_b32_e32 v82, 16, v176
	v_and_b32_e32 v83, 0xffff0000, v176
	v_lshlrev_b32_e32 v84, 16, v177
	v_and_b32_e32 v85, 0xffff0000, v177
	v_pk_mul_f32 v[90:91], v[78:79], v[82:83]
	v_pk_mul_f32 v[92:93], v[80:81], v[84:85]
	v_lshlrev_b32_e32 v78, 16, v178
	v_and_b32_e32 v79, 0xffff0000, v178
	v_lshlrev_b32_e32 v80, 16, v179
	v_and_b32_e32 v81, 0xffff0000, v179
	v_lshlrev_b32_e32 v82, 16, v180
	v_and_b32_e32 v83, 0xffff0000, v180
	v_lshlrev_b32_e32 v84, 16, v181
	v_and_b32_e32 v85, 0xffff0000, v181
	v_pk_mul_f32 v[210:211], v[78:79], v[82:83]
	v_pk_mul_f32 v[212:213], v[80:81], v[84:85]
	global_store_dwordx4 v99, v[86:89], s[42:43] offset:1024
	v_pk_mul_f32 v[90:91], v[90:91], v[94:95] op_sel_hi:[1,0]
	v_pk_mul_f32 v[92:93], v[92:93], v[94:95] op_sel_hi:[1,0]
	v_pk_mul_f32 v[210:211], v[210:211], v[94:95] op_sel:[0,1]
	v_pk_mul_f32 v[212:213], v[212:213], v[94:95] op_sel:[0,1]
	v_lshlrev_b32_e32 v78, 16, v168
	v_and_b32_e32 v79, 0xffff0000, v168
	v_lshlrev_b32_e32 v80, 16, v169
	v_and_b32_e32 v81, 0xffff0000, v169
	v_pk_mul_f32 v[214:215], v[86:87], v[136:137]
	v_pk_mul_f32 v[216:217], v[88:89], v[138:139]
	s_nop 0
	v_pk_fma_f32 v[214:215], v[90:91], v[120:121], v[214:215]
	v_pk_fma_f32 v[216:217], v[92:93], v[122:123], v[216:217]
	s_nop 0
	v_pk_fma_f32 v[214:215], v[210:211], v[104:105], v[214:215]
	v_pk_fma_f32 v[216:217], v[212:213], v[106:107], v[216:217]
	s_nop 0
	v_pk_mul_f32 v[214:215], v[214:215], v[78:79]
	v_pk_mul_f32 v[216:217], v[216:217], v[80:81]
	s_nop 0
	v_cvt_pk_bf16_f32 v218, v214, v215
	v_cvt_pk_bf16_f32 v219, v216, v217
	global_store_dwordx2 v44, v[218:219], s[34:35] offset:512
	global_load_dwordx2 v[168:169], v44, s[26:27] offset:512
	global_load_dwordx2 v[170:171], v44, s[26:27] offset:2560
	global_load_dwordx2 v[172:173], v98, s[26:27] offset:512
	global_load_dwordx2 v[174:175], v44, s[28:29] offset:2560
	global_load_dwordx2 v[176:177], v98, s[28:29] offset:512
	global_load_dwordx2 v[178:179], v44, s[30:31] offset:2560
	global_load_dwordx2 v[180:181], v98, s[30:31] offset:512
	s_waitcnt vmcnt(27)
	v_lshlrev_b32_e32 v78, 16, v184
	v_and_b32_e32 v79, 0xffff0000, v184
	v_lshlrev_b32_e32 v80, 16, v185
	v_and_b32_e32 v81, 0xffff0000, v185
	v_lshlrev_b32_e32 v82, 16, v186
	v_and_b32_e32 v83, 0xffff0000, v186
	v_lshlrev_b32_e32 v84, 16, v187
	v_and_b32_e32 v85, 0xffff0000, v187
	v_pk_mul_f32 v[86:87], v[78:79], v[82:83]
	v_pk_mul_f32 v[88:89], v[80:81], v[84:85]
	v_lshlrev_b32_e32 v78, 16, v188
	v_and_b32_e32 v79, 0xffff0000, v188
	v_lshlrev_b32_e32 v80, 16, v189
	v_and_b32_e32 v81, 0xffff0000, v189
	v_lshlrev_b32_e32 v82, 16, v190
	v_and_b32_e32 v83, 0xffff0000, v190
	v_lshlrev_b32_e32 v84, 16, v191
	v_and_b32_e32 v85, 0xffff0000, v191
	v_pk_mul_f32 v[90:91], v[78:79], v[82:83]
	v_pk_mul_f32 v[92:93], v[80:81], v[84:85]
	v_lshlrev_b32_e32 v78, 16, v192
	v_and_b32_e32 v79, 0xffff0000, v192
	v_lshlrev_b32_e32 v80, 16, v193
	v_and_b32_e32 v81, 0xffff0000, v193
	v_lshlrev_b32_e32 v82, 16, v194
	v_and_b32_e32 v83, 0xffff0000, v194
	v_lshlrev_b32_e32 v84, 16, v195
	v_and_b32_e32 v85, 0xffff0000, v195
	v_pk_mul_f32 v[210:211], v[78:79], v[82:83]
	v_pk_mul_f32 v[212:213], v[80:81], v[84:85]
	global_store_dwordx4 v99, v[86:89], s[42:43] offset:2048
	v_pk_mul_f32 v[90:91], v[90:91], v[94:95] op_sel_hi:[1,0]
	v_pk_mul_f32 v[92:93], v[92:93], v[94:95] op_sel_hi:[1,0]
	v_pk_mul_f32 v[210:211], v[210:211], v[94:95] op_sel:[0,1]
	v_pk_mul_f32 v[212:213], v[212:213], v[94:95] op_sel:[0,1]
	v_lshlrev_b32_e32 v78, 16, v182
	v_and_b32_e32 v79, 0xffff0000, v182
	v_lshlrev_b32_e32 v80, 16, v183
	v_and_b32_e32 v81, 0xffff0000, v183
	v_pk_mul_f32 v[214:215], v[86:87], v[140:141]
	v_pk_mul_f32 v[216:217], v[88:89], v[142:143]
	s_nop 0
	v_pk_fma_f32 v[214:215], v[90:91], v[124:125], v[214:215]
	v_pk_fma_f32 v[216:217], v[92:93], v[126:127], v[216:217]
	s_nop 0
	v_pk_fma_f32 v[214:215], v[210:211], v[108:109], v[214:215]
	v_pk_fma_f32 v[216:217], v[212:213], v[110:111], v[216:217]
	s_nop 0
	v_pk_mul_f32 v[214:215], v[214:215], v[78:79]
	v_pk_mul_f32 v[216:217], v[216:217], v[80:81]
	s_nop 0
	v_cvt_pk_bf16_f32 v218, v214, v215
	v_cvt_pk_bf16_f32 v219, v216, v217
	global_store_dwordx2 v44, v[218:219], s[34:35] offset:1024
	global_load_dwordx2 v[182:183], v44, s[26:27] offset:1024
	global_load_dwordx2 v[184:185], v44, s[26:27] offset:3072
	global_load_dwordx2 v[186:187], v98, s[26:27] offset:1024
	global_load_dwordx2 v[188:189], v44, s[28:29] offset:3072
	global_load_dwordx2 v[190:191], v98, s[28:29] offset:1024
	global_load_dwordx2 v[192:193], v44, s[30:31] offset:3072
	global_load_dwordx2 v[194:195], v98, s[30:31] offset:1024
	s_waitcnt vmcnt(27)
; DI unsigned pk2(float lo, float hi) { f32x2 v = {lo, hi}; bf16x2_t b = __builtin_convertvector(v, bf16x2_t); return __builtin_bit_cast(unsigned, b); }
; DI float bflo(unsigned u) { return __uint_as_float(u << 16); }
; DI float bfhi(unsigned u) { return __uint_as_float(u & 0xffff0000u); }
; DI void row_decode(int r, int& b, int& s) { if (r < RP) { b = r >> 11; s = r & 2047; } else { const int rr = r - RP; b = 16 + (rr >> 4); s = rr & 15; } }
; DI void phase_convsc(ArgsP AP) {
;     ...
;     for (int r = gw; r < RT; r += NGW) {
;         int b, s; row_decode(r, b, s); const bool samp = r >= RP; const int slen = samp ? SSEQ : SEQ;
; #pragma unroll
;         for (int j = 0; j < 4; ++j) {
;             const int c = lane * 4 + 256 * j;
;             f32x4 cx[3];
; #pragma unroll
;             for (int d = 0; d < 3; ++d) {
;                 if (s - d >= 0) { const bf16* p = BCX + (size_t)(r - d) * 3072 + c; const u32x2 cc = *(const u32x2*)(p + 1024), xx = *(const u32x2*)(p + 2048);
;                     cx[d] = (f32x4){bflo(cc.x) * bflo(xx.x), bfhi(cc.x) * bfhi(xx.x), bflo(cc.y) * bflo(xx.y), bfhi(cc.y) * bfhi(xx.y)}; }
;                 else if (samp) cx[d] = *(const f32x4*)(st + ((size_t)(b - 16) * 2 + (2 + s - d)) * DM + c);
;                 else cx[d] = (f32x4){0.f, 0.f, 0.f, 0.f};
;             }
;             const f32x4 w0 = *(const f32x4*)(cw + c), w1 = *(const f32x4*)(cw + 1024 + c), w2 = *(const f32x4*)(cw + 2048 + c);
;             const f32x4 y = w2 * cx[0] + w1 * cx[1] + w0 * cx[2];
;             const u32x2 bg = *(const u32x2*)(BCX + (size_t)r * 3072 + c);
;             u32x2 w; w.x = pk2(bflo(bg.x) * y[0], bfhi(bg.x) * y[1]); w.y = pk2(bflo(bg.y) * y[2], bfhi(bg.y) * y[3]);
;             *(u32x2*)(OA + (size_t)r * DM + c) = w;
;             if (s >= slen - 2) { float* o = samp ? AP->out + O_SCS + ((size_t)(b - 16) * 2 + (s - (slen - 2))) * DM + c : AP->out + O_SCP + ((size_t)b * 2 + (s - (slen - 2))) * DM + c; *(f32x4*)o = cx[0]; }
	v_lshlrev_b32_e32 v78, 16, v198
	v_and_b32_e32 v79, 0xffff0000, v198
	v_lshlrev_b32_e32 v80, 16, v199
	v_and_b32_e32 v81, 0xffff0000, v199
	v_lshlrev_b32_e32 v82, 16, v200
	v_and_b32_e32 v83, 0xffff0000, v200
	v_lshlrev_b32_e32 v84, 16, v201
	v_and_b32_e32 v85, 0xffff0000, v201
	v_pk_mul_f32 v[86:87], v[78:79], v[82:83]
	v_pk_mul_f32 v[88:89], v[80:81], v[84:85]
	v_lshlrev_b32_e32 v78, 16, v202
	v_and_b32_e32 v79, 0xffff0000, v202
	v_lshlrev_b32_e32 v80, 16, v203
	v_and_b32_e32 v81, 0xffff0000, v203
	v_lshlrev_b32_e32 v82, 16, v204
	v_and_b32_e32 v83, 0xffff0000, v204
	v_lshlrev_b32_e32 v84, 16, v205
	v_and_b32_e32 v85, 0xffff0000, v205
	v_pk_mul_f32 v[90:91], v[78:79], v[82:83]
	v_pk_mul_f32 v[92:93], v[80:81], v[84:85]
	v_lshlrev_b32_e32 v78, 16, v206
	v_and_b32_e32 v79, 0xffff0000, v206
	v_lshlrev_b32_e32 v80, 16, v207
	v_and_b32_e32 v81, 0xffff0000, v207
	v_lshlrev_b32_e32 v82, 16, v208
	v_and_b32_e32 v83, 0xffff0000, v208
	v_lshlrev_b32_e32 v84, 16, v209
	v_and_b32_e32 v85, 0xffff0000, v209
	v_pk_mul_f32 v[210:211], v[78:79], v[82:83]
	v_pk_mul_f32 v[212:213], v[80:81], v[84:85]
	global_store_dwordx4 v99, v[86:89], s[42:43] offset:3072
	v_pk_mul_f32 v[90:91], v[90:91], v[94:95] op_sel_hi:[1,0]
	v_pk_mul_f32 v[92:93], v[92:93], v[94:95] op_sel_hi:[1,0]
	v_pk_mul_f32 v[210:211], v[210:211], v[94:95] op_sel:[0,1]
	v_pk_mul_f32 v[212:213], v[212:213], v[94:95] op_sel:[0,1]
	v_lshlrev_b32_e32 v78, 16, v196
	v_and_b32_e32 v79, 0xffff0000, v196
	v_lshlrev_b32_e32 v80, 16, v197
	v_and_b32_e32 v81, 0xffff0000, v197
	v_pk_mul_f32 v[214:215], v[86:87], v[144:145]
	v_pk_mul_f32 v[216:217], v[88:89], v[146:147]
	s_nop 0
	v_pk_fma_f32 v[214:215], v[90:91], v[128:129], v[214:215]
	v_pk_fma_f32 v[216:217], v[92:93], v[130:131], v[216:217]
	s_nop 0
	v_pk_fma_f32 v[214:215], v[210:211], v[112:113], v[214:215]
	v_pk_fma_f32 v[216:217], v[212:213], v[114:115], v[216:217]
	s_nop 0
	v_pk_mul_f32 v[214:215], v[214:215], v[78:79]
	v_pk_mul_f32 v[216:217], v[216:217], v[80:81]
	s_nop 0
	v_cvt_pk_bf16_f32 v218, v214, v215
	v_cvt_pk_bf16_f32 v219, v216, v217
	global_store_dwordx2 v44, v[218:219], s[34:35] offset:1536
	global_load_dwordx2 v[196:197], v44, s[26:27] offset:1536
	global_load_dwordx2 v[198:199], v44, s[26:27] offset:3584
	global_load_dwordx2 v[200:201], v98, s[26:27] offset:1536
	global_load_dwordx2 v[202:203], v44, s[28:29] offset:3584
	global_load_dwordx2 v[204:205], v98, s[28:29] offset:1536
	global_load_dwordx2 v[206:207], v44, s[30:31] offset:3584
	global_load_dwordx2 v[208:209], v98, s[30:31] offset:1536
	s_add_u32 s34, s34, 0x400000
	s_addc_u32 s35, s35, 0
	s_add_u32 s42, s42, 0x2000
	s_addc_u32 s43, s43, 0
	s_add_i32 s37, s37, 1
	s_cmp_lt_u32 s37, 16
	s_cbranch_scc1 .Lcsc_row_s
.Lcsc_tail:
	s_waitcnt vmcnt(0)
	v_add_u32_e32 v12, 0x8000, v12
	s_mov_b64 s[40:41], 0x4000000
	v_lshl_add_u64 v[46:47], v[46:47], 0, s[40:41]
	s_mov_b64 s[40:41], 0xc000000
	v_lshl_add_u64 v[48:49], v[48:49], 0, s[40:41]
	s_mov_b64 s[16:17], 0
	s_cmpk_lt_u32 s36, 0x80
	s_cbranch_scc1 .LBB0_95
	s_branch .LBB0_153
.Lcsc_slow:
	s_mov_b64 s[16:17], 0
	s_branch .LBB0_95
